# hierarchical grid barrier: each of the 18 arrival/generation counters moved to its own 128-byte line (unused zeroed words of the work-queue block), shorter poll back-off
# speedup vs baseline: 1.3923x; 1.0201x over previous
; DI void grid_barrier(unsigned* bar, unsigned& epoch) {
;   __syncthreads();
;   ++epoch;
;   if (threadIdx.x == 0) {
;     __builtin_amdgcn_fence(__ATOMIC_RELEASE, "agent");
;     asm volatile("s_waitcnt vmcnt(0)" ::: "memory");
;     const unsigned target = epoch * gridDim.x;
;     __hip_atomic_fetch_add(bar, 1u, __ATOMIC_RELAXED, __HIP_MEMORY_SCOPE_AGENT);
;     unsigned spins = 0;
;     while (__hip_atomic_load(bar, __ATOMIC_RELAXED, __HIP_MEMORY_SCOPE_AGENT) < target) {
;       if (spins < 64u) __builtin_amdgcn_s_sleep(2); else __builtin_amdgcn_s_sleep(16);
;       if (++spins > (1u << 22)) break;
;     }
;     __builtin_amdgcn_fence(__ATOMIC_ACQUIRE, "agent");
;     asm volatile("s_waitcnt vmcnt(0)" ::: "memory");
;   }
;   __syncthreads();
; }
.Lmy_xbar:
	s_add_i32 s9, s6, -1
	v_readlane_b32 s10, v252, 49
	v_readlane_b32 s11, v252, 50
	s_getreg_b32 s8, hwreg(HW_REG_XCC_ID, 0, 4)
	s_and_b32 s8, s8, 7
	s_lshl_b32 s99, s8, 2
	s_lshl_b32 s8, s8, 7
	s_nop 1
	s_add_u32 s6, s10, s8
	s_addc_u32 s7, s11, 0
	s_cmp_gt_u32 s9, 1
	s_cbranch_scc1 .Lmy_xb_have
	v_mov_b32_e32 v0, s99
	global_load_dword v0, v0, s[10:11] offset:64 sc1
	s_waitcnt vmcnt(0)
	s_nop 0
	v_readfirstlane_b32 s8, v0
	s_max_u32 s8, s8, 1
	s_nop 0
	v_writelane_b32 v255, s8, 40
	s_mov_b32 s98, 0
	global_load_dword v0, v199, s[10:11] offset:64 sc1
	s_waitcnt vmcnt(0)
	s_nop 0
	v_readfirstlane_b32 s99, v0
	s_cmp_lg_u32 s99, 0
	s_cselect_b32 s99, 1, 0
	s_add_i32 s98, s98, s99
	global_load_dword v0, v199, s[10:11] offset:68 sc1
	s_waitcnt vmcnt(0)
	s_nop 0
	v_readfirstlane_b32 s99, v0
	s_cmp_lg_u32 s99, 0
	s_cselect_b32 s99, 1, 0
	s_add_i32 s98, s98, s99
	global_load_dword v0, v199, s[10:11] offset:72 sc1
	s_waitcnt vmcnt(0)
	s_nop 0
	v_readfirstlane_b32 s99, v0
	s_cmp_lg_u32 s99, 0
	s_cselect_b32 s99, 1, 0
	s_add_i32 s98, s98, s99
	global_load_dword v0, v199, s[10:11] offset:76 sc1
	s_waitcnt vmcnt(0)
	s_nop 0
	v_readfirstlane_b32 s99, v0
	s_cmp_lg_u32 s99, 0
	s_cselect_b32 s99, 1, 0
	s_add_i32 s98, s98, s99
	global_load_dword v0, v199, s[10:11] offset:80 sc1
	s_waitcnt vmcnt(0)
	s_nop 0
	v_readfirstlane_b32 s99, v0
	s_cmp_lg_u32 s99, 0
	s_cselect_b32 s99, 1, 0
	s_add_i32 s98, s98, s99
	global_load_dword v0, v199, s[10:11] offset:84 sc1
	s_waitcnt vmcnt(0)
	s_nop 0
	v_readfirstlane_b32 s99, v0
	s_cmp_lg_u32 s99, 0
	s_cselect_b32 s99, 1, 0
	s_add_i32 s98, s98, s99
	global_load_dword v0, v199, s[10:11] offset:88 sc1
	s_waitcnt vmcnt(0)
	s_nop 0
	v_readfirstlane_b32 s99, v0
	s_cmp_lg_u32 s99, 0
	s_cselect_b32 s99, 1, 0
	s_add_i32 s98, s98, s99
	global_load_dword v0, v199, s[10:11] offset:92 sc1
	s_waitcnt vmcnt(0)
	s_nop 0
	v_readfirstlane_b32 s99, v0
	s_cmp_lg_u32 s99, 0
	s_cselect_b32 s99, 1, 0
	s_add_i32 s98, s98, s99
	s_max_u32 s98, s98, 1
	s_nop 0
	v_writelane_b32 v255, s98, 41
.Lmy_xb_have:
	s_nop 1
	v_readlane_b32 s8, v255, 40
	v_readlane_b32 s98, v255, 41
	v_mov_b32_e32 v0, 1
	global_atomic_add v0, v199, v0, s[6:7] offset:-2304 sc0
	s_waitcnt vmcnt(0)
	s_nop 0
	v_readfirstlane_b32 s99, v0
	s_add_i32 s99, s99, 1
	s_mul_i32 s8, s8, s9
	s_cmp_eq_u32 s99, s8
	s_cbranch_scc0 .Lmy_xb_wait_local
	buffer_wbl2 sc1
	s_waitcnt vmcnt(0)
	v_mov_b32_e32 v0, 1
	global_atomic_add v0, v199, v0, s[10:11] offset:-256 sc0
	s_waitcnt vmcnt(0)
	s_nop 0
	v_readfirstlane_b32 s99, v0
	s_add_i32 s99, s99, 1
	s_mul_i32 s8, s98, s9
	s_cmp_eq_u32 s99, s8
	s_cbranch_scc0 .Lmy_xb_wait_top
	v_mov_b32_e32 v0, 1
	global_atomic_add v199, v0, s[10:11] offset:-128
	s_branch .Lmy_xb_release

; DI void grid_barrier(unsigned* bar, unsigned& epoch) {
;     ...
;     while (__hip_atomic_load(bar, __ATOMIC_RELAXED, __HIP_MEMORY_SCOPE_AGENT) < target) {
;       if (spins < 64u) __builtin_amdgcn_s_sleep(2); else __builtin_amdgcn_s_sleep(16);
;       if (++spins > (1u << 22)) break;
;     }
.Lmy_xb_top_loop:
	global_load_dword v0, v199, s[10:11] offset:-128 sc1
	s_waitcnt vmcnt(0)
	v_cmp_le_u32_e32 vcc, s9, v0
	s_cbranch_vccnz .Lmy_xb_release
	s_cmp_lt_u32 s8, 64
	s_cbranch_scc1 .Lmy_xb_top_fast
	s_sleep 8

; DI void grid_barrier(unsigned* bar, unsigned& epoch) {
;     ...
;     while (__hip_atomic_load(bar, __ATOMIC_RELAXED, __HIP_MEMORY_SCOPE_AGENT) < target) {
;       if (spins < 64u) __builtin_amdgcn_s_sleep(2); else __builtin_amdgcn_s_sleep(16);
;       if (++spins > (1u << 22)) break;
;     }
;     __builtin_amdgcn_fence(__ATOMIC_ACQUIRE, "agent");
;     asm volatile("s_waitcnt vmcnt(0)" ::: "memory");
;   }
.Lmy_xb_release:
	v_mov_b32_e32 v0, 1
	global_atomic_add v199, v0, s[6:7] offset:-1280
	s_branch .Lmy_to_67

; DI void grid_barrier(unsigned* bar, unsigned& epoch) {
;     ...
;     unsigned spins = 0;
;     while (__hip_atomic_load(bar, __ATOMIC_RELAXED, __HIP_MEMORY_SCOPE_AGENT) < target) {
;       if (spins < 64u) __builtin_amdgcn_s_sleep(2); else __builtin_amdgcn_s_sleep(16);
;       if (++spins > (1u << 22)) break;
;     }
.Lmy_xb_loc_loop:
	global_load_dword v0, v199, s[6:7] offset:-1280 sc1
	s_waitcnt vmcnt(0)
	v_cmp_le_u32_e32 vcc, s9, v0
	s_cbranch_vccnz .Lmy_to_67
	s_cmp_lt_u32 s8, 64
	s_cbranch_scc1 .Lmy_xb_loc_fast
	s_sleep 8
